# v19 plus accumulator zeroing before each GEMM tile done with 64 v_mov_b64 instead of 128 v_mov_b32 (8 tile headers)
# speedup vs baseline: 1.0022x; 1.0022x over previous
.LBB0_232:
	s_ashr_i32 s25, s24, 31
	s_lshl_b64 s[26:27], s[24:25], 21
	s_add_u32 s26, s46, s26
	s_addc_u32 s27, s47, s27
	s_and_b64 s[28:29], s[2:3], exec
	s_cselect_b32 s25, s27, s35
	s_cselect_b32 s64, s26, s34
	s_ashr_i32 s23, s22, 31
	s_lshl_b64 s[28:29], s[22:23], 21
	s_add_u32 s28, s48, s28
	s_addc_u32 s29, s49, s29
	s_and_b64 s[38:39], s[2:3], exec
	s_cselect_b32 s23, s29, s37
	s_cselect_b32 s65, s28, s36
	s_add_u32 s66, s36, 0x100
	s_addc_u32 s67, s37, 0
	s_add_u32 s34, s34, 0x100080
	v_mov_b64_e32 v[0:1], 0
	s_addc_u32 s35, s35, 0
	s_mov_b32 s68, -2
	v_mov_b64_e32 v[2:3], 0
	v_mov_b64_e32 v[4:5], 0
	v_mov_b64_e32 v[6:7], 0
	v_mov_b64_e32 v[12:13], 0
	v_mov_b64_e32 v[14:15], 0
	v_mov_b64_e32 v[20:21], 0
	v_mov_b64_e32 v[22:23], 0
	v_mov_b64_e32 v[28:29], 0
	v_mov_b64_e32 v[30:31], 0
	v_mov_b64_e32 v[36:37], 0
	v_mov_b64_e32 v[38:39], 0
	v_mov_b64_e32 v[44:45], 0
	v_mov_b64_e32 v[46:47], 0
	v_mov_b64_e32 v[52:53], 0
	v_mov_b64_e32 v[54:55], 0
	v_mov_b64_e32 v[8:9], 0
	v_mov_b64_e32 v[10:11], 0
	v_mov_b64_e32 v[16:17], 0
	v_mov_b64_e32 v[18:19], 0
	v_mov_b64_e32 v[24:25], 0
	v_mov_b64_e32 v[26:27], 0
	v_mov_b64_e32 v[32:33], 0
	v_mov_b64_e32 v[34:35], 0
	v_mov_b64_e32 v[40:41], 0
	v_mov_b64_e32 v[42:43], 0
	v_mov_b64_e32 v[48:49], 0
	v_mov_b64_e32 v[50:51], 0
	v_mov_b64_e32 v[56:57], 0
	v_mov_b64_e32 v[58:59], 0
	v_mov_b64_e32 v[60:61], 0
	v_mov_b64_e32 v[62:63], 0
	v_mov_b64_e32 v[64:65], 0
	v_mov_b64_e32 v[66:67], 0
	v_mov_b64_e32 v[68:69], 0
	v_mov_b64_e32 v[70:71], 0
	v_mov_b64_e32 v[80:81], 0
	v_mov_b64_e32 v[82:83], 0
	v_mov_b64_e32 v[84:85], 0
	v_mov_b64_e32 v[86:87], 0
	v_mov_b64_e32 v[96:97], 0
	v_mov_b64_e32 v[98:99], 0
	v_mov_b64_e32 v[100:101], 0
	v_mov_b64_e32 v[102:103], 0
	v_mov_b64_e32 v[112:113], 0
	v_mov_b64_e32 v[114:115], 0
	v_mov_b64_e32 v[116:117], 0
	v_mov_b64_e32 v[118:119], 0
	v_mov_b64_e32 v[72:73], 0
	v_mov_b64_e32 v[74:75], 0
	v_mov_b64_e32 v[76:77], 0
	v_mov_b64_e32 v[78:79], 0
	v_mov_b64_e32 v[88:89], 0
	v_mov_b64_e32 v[90:91], 0
	v_mov_b64_e32 v[92:93], 0
	v_mov_b64_e32 v[94:95], 0
	v_mov_b64_e32 v[104:105], 0
	v_mov_b64_e32 v[106:107], 0
	v_mov_b64_e32 v[108:109], 0
	v_mov_b64_e32 v[110:111], 0
	v_mov_b64_e32 v[120:121], 0
	v_mov_b64_e32 v[122:123], 0
	v_mov_b64_e32 v[124:125], 0
	v_mov_b64_e32 v[126:127], 0
	s_cmp_lt_u32 s81, 4
	s_cbranch_scc0 .Lsp_skip0
	s_setprio 1

.LBB0_253:
	s_add_u32 s65, s26, 0x100
	v_mov_b64_e32 v[0:1], 0
	s_addc_u32 s66, s27, 0
	s_mov_b32 s67, -2
	v_mov_b64_e32 v[2:3], 0
	v_mov_b64_e32 v[4:5], 0
	v_mov_b64_e32 v[6:7], 0
	v_mov_b64_e32 v[8:9], 0
	v_mov_b64_e32 v[10:11], 0
	v_mov_b64_e32 v[16:17], 0
	v_mov_b64_e32 v[18:19], 0
	v_mov_b64_e32 v[24:25], 0
	v_mov_b64_e32 v[26:27], 0
	v_mov_b64_e32 v[32:33], 0
	v_mov_b64_e32 v[34:35], 0
	v_mov_b64_e32 v[40:41], 0
	v_mov_b64_e32 v[42:43], 0
	v_mov_b64_e32 v[48:49], 0
	v_mov_b64_e32 v[50:51], 0
	v_mov_b64_e32 v[12:13], 0
	v_mov_b64_e32 v[14:15], 0
	v_mov_b64_e32 v[20:21], 0
	v_mov_b64_e32 v[22:23], 0
	v_mov_b64_e32 v[28:29], 0
	v_mov_b64_e32 v[30:31], 0
	v_mov_b64_e32 v[36:37], 0
	v_mov_b64_e32 v[38:39], 0
	v_mov_b64_e32 v[44:45], 0
	v_mov_b64_e32 v[46:47], 0
	v_mov_b64_e32 v[52:53], 0
	v_mov_b64_e32 v[54:55], 0
	v_mov_b64_e32 v[56:57], 0
	v_mov_b64_e32 v[58:59], 0
	v_mov_b64_e32 v[60:61], 0
	v_mov_b64_e32 v[62:63], 0
	v_mov_b64_e32 v[64:65], 0
	v_mov_b64_e32 v[66:67], 0
	v_mov_b64_e32 v[68:69], 0
	v_mov_b64_e32 v[70:71], 0
	v_mov_b64_e32 v[72:73], 0
	v_mov_b64_e32 v[74:75], 0
	v_mov_b64_e32 v[80:81], 0
	v_mov_b64_e32 v[82:83], 0
	v_mov_b64_e32 v[88:89], 0
	v_mov_b64_e32 v[90:91], 0
	v_mov_b64_e32 v[96:97], 0
	v_mov_b64_e32 v[98:99], 0
	v_mov_b64_e32 v[104:105], 0
	v_mov_b64_e32 v[106:107], 0
	v_mov_b64_e32 v[112:113], 0
	v_mov_b64_e32 v[114:115], 0
	v_mov_b64_e32 v[76:77], 0
	v_mov_b64_e32 v[78:79], 0
	v_mov_b64_e32 v[84:85], 0
	v_mov_b64_e32 v[86:87], 0
	v_mov_b64_e32 v[92:93], 0
	v_mov_b64_e32 v[94:95], 0
	v_mov_b64_e32 v[100:101], 0
	v_mov_b64_e32 v[102:103], 0
	v_mov_b64_e32 v[108:109], 0
	v_mov_b64_e32 v[110:111], 0
	v_mov_b64_e32 v[116:117], 0
	v_mov_b64_e32 v[118:119], 0
	v_mov_b64_e32 v[120:121], 0
	v_mov_b64_e32 v[122:123], 0
	v_mov_b64_e32 v[124:125], 0
	v_mov_b64_e32 v[126:127], 0
	s_cmp_lt_u32 s81, 4
	s_cbranch_scc0 .Lsp_skip1
	s_setprio 1

.LBB0_280:
	s_ashr_i32 s23, s22, 31
	s_lshl_b64 s[24:25], s[22:23], 20
	s_add_u32 s24, s39, s24
	s_addc_u32 s25, s45, s25
	s_and_b64 s[26:27], s[2:3], exec
	s_cselect_b32 s23, s25, s35
	s_cselect_b32 s57, s24, s34
	s_ashr_i32 s21, s20, 31
	s_lshl_b64 s[26:27], s[20:21], 20
	s_add_u32 s26, s46, s26
	s_addc_u32 s27, s47, s27
	s_and_b64 s[36:37], s[2:3], exec
	s_cselect_b32 s21, s27, s31
	s_cselect_b32 s58, s26, s30
	s_add_u32 s59, s30, 0x100
	s_addc_u32 s60, s31, 0
	s_add_u32 s30, s34, 0x80080
	v_mov_b64_e32 v[0:1], 0
	s_addc_u32 s31, s35, 0
	s_mov_b32 s61, -2
	v_mov_b64_e32 v[2:3], 0
	v_mov_b64_e32 v[4:5], 0
	v_mov_b64_e32 v[6:7], 0
	v_mov_b64_e32 v[16:17], 0
	v_mov_b64_e32 v[18:19], 0
	v_mov_b64_e32 v[20:21], 0
	v_mov_b64_e32 v[22:23], 0
	v_mov_b64_e32 v[32:33], 0
	v_mov_b64_e32 v[34:35], 0
	v_mov_b64_e32 v[36:37], 0
	v_mov_b64_e32 v[38:39], 0
	v_mov_b64_e32 v[48:49], 0
	v_mov_b64_e32 v[50:51], 0
	v_mov_b64_e32 v[52:53], 0
	v_mov_b64_e32 v[54:55], 0
	v_mov_b64_e32 v[8:9], 0
	v_mov_b64_e32 v[10:11], 0
	v_mov_b64_e32 v[12:13], 0
	v_mov_b64_e32 v[14:15], 0
	v_mov_b64_e32 v[24:25], 0
	v_mov_b64_e32 v[26:27], 0
	v_mov_b64_e32 v[28:29], 0
	v_mov_b64_e32 v[30:31], 0
	v_mov_b64_e32 v[40:41], 0
	v_mov_b64_e32 v[42:43], 0
	v_mov_b64_e32 v[44:45], 0
	v_mov_b64_e32 v[46:47], 0
	v_mov_b64_e32 v[56:57], 0
	v_mov_b64_e32 v[58:59], 0
	v_mov_b64_e32 v[60:61], 0
	v_mov_b64_e32 v[62:63], 0
	v_mov_b64_e32 v[64:65], 0
	v_mov_b64_e32 v[66:67], 0
	v_mov_b64_e32 v[68:69], 0
	v_mov_b64_e32 v[70:71], 0
	v_mov_b64_e32 v[80:81], 0
	v_mov_b64_e32 v[82:83], 0
	v_mov_b64_e32 v[84:85], 0
	v_mov_b64_e32 v[86:87], 0
	v_mov_b64_e32 v[96:97], 0
	v_mov_b64_e32 v[98:99], 0
	v_mov_b64_e32 v[100:101], 0
	v_mov_b64_e32 v[102:103], 0
	v_mov_b64_e32 v[112:113], 0
	v_mov_b64_e32 v[114:115], 0
	v_mov_b64_e32 v[116:117], 0
	v_mov_b64_e32 v[118:119], 0
	v_mov_b64_e32 v[72:73], 0
	v_mov_b64_e32 v[74:75], 0
	v_mov_b64_e32 v[76:77], 0
	v_mov_b64_e32 v[78:79], 0
	v_mov_b64_e32 v[88:89], 0
	v_mov_b64_e32 v[90:91], 0
	v_mov_b64_e32 v[92:93], 0
	v_mov_b64_e32 v[94:95], 0
	v_mov_b64_e32 v[104:105], 0
	v_mov_b64_e32 v[106:107], 0
	v_mov_b64_e32 v[108:109], 0
	v_mov_b64_e32 v[110:111], 0
	v_mov_b64_e32 v[120:121], 0
	v_mov_b64_e32 v[122:123], 0
	v_mov_b64_e32 v[124:125], 0
	v_mov_b64_e32 v[126:127], 0
	s_cmp_lt_u32 s81, 4
	s_cbranch_scc0 .Lsp_skip2
	s_setprio 1

.LBB0_450:
	s_ashr_i32 s21, s20, 31
	s_lshl_b64 s[22:23], s[20:21], 21
	s_add_u32 s22, s33, s22
	s_addc_u32 s23, s38, s23
	s_and_b64 s[24:25], s[4:5], exec
	s_cselect_b32 s21, s23, s35
	s_cselect_b32 s27, s22, s34
	s_ashr_i32 s19, s18, 31
	s_lshl_b64 s[24:25], s[18:19], 21
	s_add_u32 s24, s39, s24
	s_addc_u32 s25, s40, s25
	s_and_b64 s[36:37], s[4:5], exec
	s_cselect_b32 s19, s25, s31
	s_cselect_b32 s55, s24, s30
	s_add_u32 s56, s30, 0x100
	s_addc_u32 s57, s31, 0
	s_add_u32 s30, s34, 0x100080
	v_mov_b64_e32 v[0:1], 0
	s_addc_u32 s31, s35, 0
	s_mov_b32 s58, -2
	s_waitcnt lgkmcnt(0)
	v_mov_b64_e32 v[2:3], 0
	v_mov_b64_e32 v[4:5], 0
	v_mov_b64_e32 v[6:7], 0
	v_mov_b64_e32 v[16:17], 0
	v_mov_b64_e32 v[18:19], 0
	v_mov_b64_e32 v[20:21], 0
	v_mov_b64_e32 v[22:23], 0
	v_mov_b64_e32 v[32:33], 0
	v_mov_b64_e32 v[34:35], 0
	v_mov_b64_e32 v[36:37], 0
	v_mov_b64_e32 v[38:39], 0
	v_mov_b64_e32 v[48:49], 0
	v_mov_b64_e32 v[50:51], 0
	v_mov_b64_e32 v[52:53], 0
	v_mov_b64_e32 v[54:55], 0
	v_mov_b64_e32 v[8:9], 0
	v_mov_b64_e32 v[10:11], 0
	v_mov_b64_e32 v[12:13], 0
	v_mov_b64_e32 v[14:15], 0
	v_mov_b64_e32 v[24:25], 0
	v_mov_b64_e32 v[26:27], 0
	v_mov_b64_e32 v[28:29], 0
	v_mov_b64_e32 v[30:31], 0
	v_mov_b64_e32 v[40:41], 0
	v_mov_b64_e32 v[42:43], 0
	v_mov_b64_e32 v[44:45], 0
	v_mov_b64_e32 v[46:47], 0
	v_mov_b64_e32 v[56:57], 0
	v_mov_b64_e32 v[58:59], 0
	v_mov_b64_e32 v[60:61], 0
	v_mov_b64_e32 v[62:63], 0
	v_mov_b64_e32 v[64:65], 0
	v_mov_b64_e32 v[66:67], 0
	v_mov_b64_e32 v[68:69], 0
	v_mov_b64_e32 v[70:71], 0
	v_mov_b64_e32 v[80:81], 0
	v_mov_b64_e32 v[82:83], 0
	v_mov_b64_e32 v[84:85], 0
	v_mov_b64_e32 v[86:87], 0
	v_mov_b64_e32 v[96:97], 0
	v_mov_b64_e32 v[98:99], 0
	v_mov_b64_e32 v[100:101], 0
	v_mov_b64_e32 v[102:103], 0
	v_mov_b64_e32 v[116:117], 0
	v_mov_b64_e32 v[118:119], 0
	v_mov_b64_e32 v[120:121], 0
	v_mov_b64_e32 v[122:123], 0
	v_mov_b64_e32 v[72:73], 0
	v_mov_b64_e32 v[74:75], 0
	v_mov_b64_e32 v[76:77], 0
	v_mov_b64_e32 v[78:79], 0
	v_mov_b64_e32 v[88:89], 0
	v_mov_b64_e32 v[90:91], 0
	v_mov_b64_e32 v[92:93], 0
	v_mov_b64_e32 v[94:95], 0
	v_mov_b64_e32 v[104:105], 0
	v_mov_b64_e32 v[106:107], 0
	v_mov_b64_e32 v[108:109], 0
	v_mov_b64_e32 v[110:111], 0
	v_mov_b64_e32 v[128:129], 0
	v_mov_b64_e32 v[130:131], 0
	v_mov_b64_e32 v[132:133], 0
	v_mov_b64_e32 v[134:135], 0
	s_cmp_lt_u32 s81, 4
	s_cbranch_scc0 .Lsp_skip3
	s_setprio 1

.LBB0_549:
	s_ashr_i32 s31, s30, 31
	s_lshl_b64 s[34:35], s[30:31], 20
	s_add_u32 s34, s40, s34
	s_addc_u32 s35, s41, s35
	s_and_b64 s[36:37], s[2:3], exec
	s_cselect_b32 s1, s35, s7
	s_cselect_b32 s31, s34, s6
	s_ashr_i32 s29, s28, 31
	s_lshl_b64 s[36:37], s[28:29], 20
	s_add_u32 s36, s42, s36
	s_addc_u32 s37, s43, s37
	s_and_b64 s[38:39], s[2:3], exec
	s_cselect_b32 s29, s37, s5
	s_cselect_b32 s61, s36, s4
	s_add_u32 s62, s4, 0x100
	s_addc_u32 s63, s5, 0
	s_add_u32 s4, s6, 0x80080
	v_mov_b64_e32 v[0:1], 0
	s_addc_u32 s5, s7, 0
	s_mov_b32 s64, -2
	v_mov_b64_e32 v[2:3], 0
	v_mov_b64_e32 v[4:5], 0
	v_mov_b64_e32 v[6:7], 0
	v_mov_b64_e32 v[16:17], 0
	v_mov_b64_e32 v[18:19], 0
	v_mov_b64_e32 v[20:21], 0
	v_mov_b64_e32 v[22:23], 0
	v_mov_b64_e32 v[32:33], 0
	v_mov_b64_e32 v[34:35], 0
	v_mov_b64_e32 v[36:37], 0
	v_mov_b64_e32 v[38:39], 0
	v_mov_b64_e32 v[48:49], 0
	v_mov_b64_e32 v[50:51], 0
	v_mov_b64_e32 v[52:53], 0
	v_mov_b64_e32 v[54:55], 0
	v_mov_b64_e32 v[8:9], 0
	v_mov_b64_e32 v[10:11], 0
	v_mov_b64_e32 v[12:13], 0
	v_mov_b64_e32 v[14:15], 0
	v_mov_b64_e32 v[24:25], 0
	v_mov_b64_e32 v[26:27], 0
	v_mov_b64_e32 v[28:29], 0
	v_mov_b64_e32 v[30:31], 0
	v_mov_b64_e32 v[40:41], 0
	v_mov_b64_e32 v[42:43], 0
	v_mov_b64_e32 v[44:45], 0
	v_mov_b64_e32 v[46:47], 0
	v_mov_b64_e32 v[56:57], 0
	v_mov_b64_e32 v[58:59], 0
	v_mov_b64_e32 v[60:61], 0
	v_mov_b64_e32 v[62:63], 0
	v_mov_b64_e32 v[64:65], 0
	v_mov_b64_e32 v[66:67], 0
	v_mov_b64_e32 v[68:69], 0
	v_mov_b64_e32 v[70:71], 0
	v_mov_b64_e32 v[80:81], 0
	v_mov_b64_e32 v[82:83], 0
	v_mov_b64_e32 v[84:85], 0
	v_mov_b64_e32 v[86:87], 0
	v_mov_b64_e32 v[96:97], 0
	v_mov_b64_e32 v[98:99], 0
	v_mov_b64_e32 v[100:101], 0
	v_mov_b64_e32 v[102:103], 0
	v_mov_b64_e32 v[112:113], 0
	v_mov_b64_e32 v[114:115], 0
	v_mov_b64_e32 v[116:117], 0
	v_mov_b64_e32 v[118:119], 0
	v_mov_b64_e32 v[72:73], 0
	v_mov_b64_e32 v[74:75], 0
	v_mov_b64_e32 v[76:77], 0
	v_mov_b64_e32 v[78:79], 0
	v_mov_b64_e32 v[88:89], 0
	v_mov_b64_e32 v[90:91], 0
	v_mov_b64_e32 v[92:93], 0
	v_mov_b64_e32 v[94:95], 0
	v_mov_b64_e32 v[104:105], 0
	v_mov_b64_e32 v[106:107], 0
	v_mov_b64_e32 v[108:109], 0
	v_mov_b64_e32 v[110:111], 0
	v_mov_b64_e32 v[120:121], 0
	v_mov_b64_e32 v[122:123], 0
	v_mov_b64_e32 v[124:125], 0
	v_mov_b64_e32 v[126:127], 0
	s_cmp_lt_u32 s81, 4
	s_cbranch_scc0 .Lsp_skip4
	s_setprio 1

.LBB0_634:
	s_ashr_i32 s21, s20, 31
	s_mul_i32 s22, s20, 0x810000
	s_mov_b32 s23, 0
	s_add_u32 s22, s33, s22
	s_addc_u32 s23, s38, s23
	s_and_b64 s[24:25], s[4:5], exec
	s_cselect_b32 s21, s23, s35
	s_cselect_b32 s27, s22, s34
	s_ashr_i32 s19, s18, 31
	s_lshl_b64 s[24:25], s[18:19], 23
	s_add_u32 s24, s39, s24
	s_addc_u32 s25, s40, s25
	s_and_b64 s[36:37], s[4:5], exec
	s_cselect_b32 s19, s25, s31
	s_cselect_b32 s55, s24, s30
	s_add_u32 s56, s30, 0x100
	s_addc_u32 s57, s31, 0
	s_add_u32 s30, s34, 0x408080
	v_mov_b64_e32 v[0:1], 0
	s_addc_u32 s31, s35, 0
	s_mov_b32 s58, -2
	s_waitcnt lgkmcnt(0)
	v_mov_b64_e32 v[2:3], 0
	v_mov_b64_e32 v[4:5], 0
	v_mov_b64_e32 v[6:7], 0
	v_mov_b64_e32 v[16:17], 0
	v_mov_b64_e32 v[18:19], 0
	v_mov_b64_e32 v[20:21], 0
	v_mov_b64_e32 v[22:23], 0
	v_mov_b64_e32 v[32:33], 0
	v_mov_b64_e32 v[34:35], 0
	v_mov_b64_e32 v[36:37], 0
	v_mov_b64_e32 v[38:39], 0
	v_mov_b64_e32 v[48:49], 0
	v_mov_b64_e32 v[50:51], 0
	v_mov_b64_e32 v[52:53], 0
	v_mov_b64_e32 v[54:55], 0
	v_mov_b64_e32 v[8:9], 0
	v_mov_b64_e32 v[10:11], 0
	v_mov_b64_e32 v[12:13], 0
	v_mov_b64_e32 v[14:15], 0
	v_mov_b64_e32 v[24:25], 0
	v_mov_b64_e32 v[26:27], 0
	v_mov_b64_e32 v[28:29], 0
	v_mov_b64_e32 v[30:31], 0
	v_mov_b64_e32 v[40:41], 0
	v_mov_b64_e32 v[42:43], 0
	v_mov_b64_e32 v[44:45], 0
	v_mov_b64_e32 v[46:47], 0
	v_mov_b64_e32 v[56:57], 0
	v_mov_b64_e32 v[58:59], 0
	v_mov_b64_e32 v[60:61], 0
	v_mov_b64_e32 v[62:63], 0
	v_mov_b64_e32 v[64:65], 0
	v_mov_b64_e32 v[66:67], 0
	v_mov_b64_e32 v[68:69], 0
	v_mov_b64_e32 v[70:71], 0
	v_mov_b64_e32 v[80:81], 0
	v_mov_b64_e32 v[82:83], 0
	v_mov_b64_e32 v[84:85], 0
	v_mov_b64_e32 v[86:87], 0
	v_mov_b64_e32 v[96:97], 0
	v_mov_b64_e32 v[98:99], 0
	v_mov_b64_e32 v[100:101], 0
	v_mov_b64_e32 v[102:103], 0
	v_mov_b64_e32 v[116:117], 0
	v_mov_b64_e32 v[118:119], 0
	v_mov_b64_e32 v[120:121], 0
	v_mov_b64_e32 v[122:123], 0
	v_mov_b64_e32 v[72:73], 0
	v_mov_b64_e32 v[74:75], 0
	v_mov_b64_e32 v[76:77], 0
	v_mov_b64_e32 v[78:79], 0
	v_mov_b64_e32 v[88:89], 0
	v_mov_b64_e32 v[90:91], 0
	v_mov_b64_e32 v[92:93], 0
	v_mov_b64_e32 v[94:95], 0
	v_mov_b64_e32 v[104:105], 0
	v_mov_b64_e32 v[106:107], 0
	v_mov_b64_e32 v[108:109], 0
	v_mov_b64_e32 v[110:111], 0
	v_mov_b64_e32 v[128:129], 0
	v_mov_b64_e32 v[130:131], 0
	v_mov_b64_e32 v[132:133], 0
	v_mov_b64_e32 v[134:135], 0
	s_cmp_lt_u32 s81, 4
	s_cbranch_scc0 .Lsp_skip5
	s_setprio 1

.LBB0_725:
	s_ashr_i32 s23, s22, 31
	s_lshl_b64 s[24:25], s[22:23], 20
	s_add_u32 s24, s30, s24
	s_addc_u32 s25, s31, s25
	s_and_b64 s[26:27], s[2:3], exec
	s_cselect_b32 s1, s25, s7
	s_cselect_b32 s23, s24, s6
	s_ashr_i32 s21, s20, 31
	s_lshl_b64 s[26:27], s[20:21], 20
	s_add_u32 s26, s33, s26
	s_addc_u32 s27, s34, s27
	s_and_b64 s[28:29], s[2:3], exec
	s_cselect_b32 s21, s27, s5
	s_cselect_b32 s51, s26, s4
	s_add_u32 s52, s4, 0x100
	s_addc_u32 s53, s5, 0
	s_add_u32 s4, s6, 0x80080
	v_mov_b64_e32 v[0:1], 0
	s_addc_u32 s5, s7, 0
	s_mov_b32 s54, -2
	v_mov_b64_e32 v[2:3], 0
	v_mov_b64_e32 v[4:5], 0
	v_mov_b64_e32 v[6:7], 0
	v_mov_b64_e32 v[16:17], 0
	v_mov_b64_e32 v[18:19], 0
	v_mov_b64_e32 v[20:21], 0
	v_mov_b64_e32 v[22:23], 0
	v_mov_b64_e32 v[32:33], 0
	v_mov_b64_e32 v[34:35], 0
	v_mov_b64_e32 v[36:37], 0
	v_mov_b64_e32 v[38:39], 0
	v_mov_b64_e32 v[48:49], 0
	v_mov_b64_e32 v[50:51], 0
	v_mov_b64_e32 v[52:53], 0
	v_mov_b64_e32 v[54:55], 0
	v_mov_b64_e32 v[8:9], 0
	v_mov_b64_e32 v[10:11], 0
	v_mov_b64_e32 v[12:13], 0
	v_mov_b64_e32 v[14:15], 0
	v_mov_b64_e32 v[24:25], 0
	v_mov_b64_e32 v[26:27], 0
	v_mov_b64_e32 v[28:29], 0
	v_mov_b64_e32 v[30:31], 0
	v_mov_b64_e32 v[40:41], 0
	v_mov_b64_e32 v[42:43], 0
	v_mov_b64_e32 v[44:45], 0
	v_mov_b64_e32 v[46:47], 0
	v_mov_b64_e32 v[56:57], 0
	v_mov_b64_e32 v[58:59], 0
	v_mov_b64_e32 v[60:61], 0
	v_mov_b64_e32 v[62:63], 0
	v_mov_b64_e32 v[64:65], 0
	v_mov_b64_e32 v[66:67], 0
	v_mov_b64_e32 v[68:69], 0
	v_mov_b64_e32 v[70:71], 0
	v_mov_b64_e32 v[80:81], 0
	v_mov_b64_e32 v[82:83], 0
	v_mov_b64_e32 v[84:85], 0
	v_mov_b64_e32 v[86:87], 0
	v_mov_b64_e32 v[96:97], 0
	v_mov_b64_e32 v[98:99], 0
	v_mov_b64_e32 v[100:101], 0
	v_mov_b64_e32 v[102:103], 0
	v_mov_b64_e32 v[112:113], 0
	v_mov_b64_e32 v[114:115], 0
	v_mov_b64_e32 v[116:117], 0
	v_mov_b64_e32 v[118:119], 0
	v_mov_b64_e32 v[72:73], 0
	v_mov_b64_e32 v[74:75], 0
	v_mov_b64_e32 v[76:77], 0
	v_mov_b64_e32 v[78:79], 0
	v_mov_b64_e32 v[88:89], 0
	v_mov_b64_e32 v[90:91], 0
	v_mov_b64_e32 v[92:93], 0
	v_mov_b64_e32 v[94:95], 0
	v_mov_b64_e32 v[104:105], 0
	v_mov_b64_e32 v[106:107], 0
	v_mov_b64_e32 v[108:109], 0
	v_mov_b64_e32 v[110:111], 0
	v_mov_b64_e32 v[120:121], 0
	v_mov_b64_e32 v[122:123], 0
	v_mov_b64_e32 v[124:125], 0
	v_mov_b64_e32 v[126:127], 0
	s_cmp_lt_u32 s81, 4
	s_cbranch_scc0 .Lsp_skip6
	s_setprio 1

.LBB0_1355:
	s_ashr_i32 s23, s22, 31
	s_lshl_b64 s[24:25], s[22:23], 20
	s_add_u32 s24, s38, s24
	s_addc_u32 s25, s39, s25
	s_and_b64 s[26:27], s[2:3], exec
	s_cselect_b32 s1, s25, s35
	s_cselect_b32 s23, s24, s34
	s_ashr_i32 s21, s20, 31
	s_lshl_b64 s[26:27], s[20:21], 20
	s_add_u32 s26, s40, s26
	s_addc_u32 s27, s41, s27
	s_and_b64 s[36:37], s[2:3], exec
	s_cselect_b32 s21, s27, s31
	s_cselect_b32 s29, s26, s30
	s_add_u32 s33, s30, 0x100
	s_addc_u32 s57, s31, 0
	s_add_u32 s30, s34, 0x80080
	v_mov_b64_e32 v[0:1], 0
	s_addc_u32 s31, s35, 0
	s_mov_b32 s58, -2
	v_mov_b64_e32 v[2:3], 0
	v_mov_b64_e32 v[4:5], 0
	v_mov_b64_e32 v[6:7], 0
	v_mov_b64_e32 v[16:17], 0
	v_mov_b64_e32 v[18:19], 0
	v_mov_b64_e32 v[20:21], 0
	v_mov_b64_e32 v[22:23], 0
	v_mov_b64_e32 v[32:33], 0
	v_mov_b64_e32 v[34:35], 0
	v_mov_b64_e32 v[36:37], 0
	v_mov_b64_e32 v[38:39], 0
	v_mov_b64_e32 v[48:49], 0
	v_mov_b64_e32 v[50:51], 0
	v_mov_b64_e32 v[52:53], 0
	v_mov_b64_e32 v[54:55], 0
	v_mov_b64_e32 v[8:9], 0
	v_mov_b64_e32 v[10:11], 0
	v_mov_b64_e32 v[12:13], 0
	v_mov_b64_e32 v[14:15], 0
	v_mov_b64_e32 v[24:25], 0
	v_mov_b64_e32 v[26:27], 0
	v_mov_b64_e32 v[28:29], 0
	v_mov_b64_e32 v[30:31], 0
	v_mov_b64_e32 v[40:41], 0
	v_mov_b64_e32 v[42:43], 0
	v_mov_b64_e32 v[44:45], 0
	v_mov_b64_e32 v[46:47], 0
	v_mov_b64_e32 v[56:57], 0
	v_mov_b64_e32 v[58:59], 0
	v_mov_b64_e32 v[60:61], 0
	v_mov_b64_e32 v[62:63], 0
	v_mov_b64_e32 v[64:65], 0
	v_mov_b64_e32 v[66:67], 0
	v_mov_b64_e32 v[68:69], 0
	v_mov_b64_e32 v[70:71], 0
	v_mov_b64_e32 v[80:81], 0
	v_mov_b64_e32 v[82:83], 0
	v_mov_b64_e32 v[84:85], 0
	v_mov_b64_e32 v[86:87], 0
	v_mov_b64_e32 v[96:97], 0
	v_mov_b64_e32 v[98:99], 0
	v_mov_b64_e32 v[100:101], 0
	v_mov_b64_e32 v[102:103], 0
	v_mov_b64_e32 v[112:113], 0
	v_mov_b64_e32 v[114:115], 0
	v_mov_b64_e32 v[116:117], 0
	v_mov_b64_e32 v[118:119], 0
	v_mov_b64_e32 v[72:73], 0
	v_mov_b64_e32 v[74:75], 0
	v_mov_b64_e32 v[76:77], 0
	v_mov_b64_e32 v[78:79], 0
	v_mov_b64_e32 v[88:89], 0
	v_mov_b64_e32 v[90:91], 0
	v_mov_b64_e32 v[92:93], 0
	v_mov_b64_e32 v[94:95], 0
	v_mov_b64_e32 v[104:105], 0
	v_mov_b64_e32 v[106:107], 0
	v_mov_b64_e32 v[108:109], 0
	v_mov_b64_e32 v[110:111], 0
	v_mov_b64_e32 v[120:121], 0
	v_mov_b64_e32 v[122:123], 0
	v_mov_b64_e32 v[124:125], 0
	v_mov_b64_e32 v[126:127], 0
	s_cmp_lt_u32 s81, 4
	s_cbranch_scc0 .Lsp_skip8
	s_setprio 1
